# group B: DMA issue back at top of iteration (hidden under partner MFMA phase)
# baseline (speedup 1.0000x reference)
; DI void diff_core(unsigned char* smem, const u16* qptr, const u16* kbase, const u16* vtbase, int vld,
;                   int ntb, int ntw, int nvalid, int ks0, const float* lut, int qpos, bool active, bool grpB,
;                   f32x16 (&O)[4], float& l_out) {
;     ...
;     float mx = S[0][0];
; #pragma unroll
;     for (int kb = 0; kb < 2; ++kb)
; #pragma unroll
;       for (int i = 0; i < 16; ++i) mx = fmaxf(mx, S[kb][i]);
;     {
;       const unsigned um = __float_as_uint(mx);
;       const auto sw = __builtin_amdgcn_permlane32_swap(um, um, false, false);
;       mx = fmaxf(__uint_as_float(sw[0]), __uint_as_float(sw[1]));
;     }
;     if (t == 0) {
;       m = mx;
; #pragma unroll
;       for (int kb = 0; kb < 2; ++kb)
; #pragma unroll
;         for (int i = 0; i < 16; ++i) S[kb][i] -= mx;
;     } else if (__any(mx > 8.f)) {
;       const float d = fmaxf(mx, 0.f);
;       const float alpha = __builtin_amdgcn_exp2f(-d);
;       m += d;
;       l *= alpha;
; #pragma unroll
;       for (int tt = 0; tt < 4; ++tt)
; #pragma unroll
;         for (int e = 0; e < 16; ++e) O[tt][e] *= alpha;
; #pragma unroll
;       for (int kb = 0; kb < 2; ++kb)
; #pragma unroll
;         for (int i = 0; i < 16; ++i) S[kb][i] -= d;
;     }
;     float ps = 0.f;
; #pragma unroll
;     for (int kb = 0; kb < 2; ++kb)
; #pragma unroll
;       for (int i = 0; i < 16; ++i) {
;         const float pe = __builtin_amdgcn_exp2f(S[kb][i]);
;         S[kb][i] = pe;
;         ps += pe;
;       }
;     l += ps;
; #pragma unroll
;     for (int kb = 0; kb < 2; ++kb)
; #pragma unroll
;       for (int s2 = 0; s2 < 2; ++s2) {
;         u32x4 pk;
;         pk.x = pack2(S[kb][8 * s2 + 0], S[kb][8 * s2 + 1]);
;         pk.y = pack2(S[kb][8 * s2 + 2], S[kb][8 * s2 + 3]);
;         pk.z = pack2(S[kb][8 * s2 + 4], S[kb][8 * s2 + 5]);
;         pk.w = pack2(S[kb][8 * s2 + 6], S[kb][8 * s2 + 7]);
;         P[kb * 2 + s2] = pk;
;       }
;     ...
;     for (int t = 0; t <= ntb; ++t) {
;       const bool act_t = active && (t < ntw);
;       { const int tn = t + 2; dma(tn < tlast ? tn : tlast, tn & 3); }
;       if (act_t) softmax(t);
;       asm volatile("s_waitcnt vmcnt(4)" ::: "memory");
;       D_BAR;
;       if (act_t) pv(t & 3);
;       __builtin_amdgcn_sched_barrier(0);
;       if (active && (t + 1) < ntw) qk((t + 1) & 3);
.LBB0_373:
	v_max_f32_e32 v0, v65, v65
	v_max_f32_e32 v1, v64, v64
	v_max_f32_e32 v0, v1, v0
	v_max3_f32 v0, v0, v66, v67
	v_max3_f32 v0, v0, v68, v69
	v_max3_f32 v0, v0, v70, v71
	v_max3_f32 v0, v0, v72, v73
	v_max3_f32 v0, v0, v74, v75
	v_max3_f32 v0, v0, v76, v77
	v_max3_f32 v0, v0, v78, v79
	v_max3_f32 v0, v0, v80, v81
	v_max3_f32 v0, v0, v82, v83
	v_max3_f32 v0, v0, v84, v85
	v_max3_f32 v0, v0, v86, v87
	v_max3_f32 v0, v0, v88, v89
	v_max3_f32 v0, v0, v90, v91
	v_max3_f32 v0, v0, v92, v93
	v_max3_f32 v0, v0, v94, v95
	v_mov_b32_e32 v1, v0
	s_nop 1
	v_permlane32_swap_b32_e32 v0, v1
	v_max_f32_e32 v1, v1, v1
	v_max_f32_e32 v0, v0, v0
	v_max_f32_e32 v189, v0, v1
	v_xor_b32_e32 v232, 0x80000000, v189
	v_mov_b32_e32 v233, v232
	v_mov_b32_e32 v234, v232
	v_mov_b32_e32 v235, v232
	v_mov_b32_e32 v236, v232
	v_mov_b32_e32 v237, v232
	v_mov_b32_e32 v238, v232
	v_mov_b32_e32 v239, v232
	v_mov_b32_e32 v240, v232
	v_mov_b32_e32 v241, v232
	v_mov_b32_e32 v242, v232
	v_mov_b32_e32 v243, v232
	v_mov_b32_e32 v244, v232
	v_mov_b32_e32 v245, v232
	v_mov_b32_e32 v246, v232
	v_mov_b32_e32 v247, v232
	v_sub_f32_e32 v0, v80, v189
	v_sub_f32_e32 v1, v81, v189
	v_sub_f32_e32 v2, v82, v189
	v_sub_f32_e32 v3, v83, v189
	v_sub_f32_e32 v4, v84, v189
	v_sub_f32_e32 v5, v85, v189
	v_sub_f32_e32 v6, v86, v189
	v_sub_f32_e32 v7, v87, v189
	v_sub_f32_e32 v8, v88, v189
	v_sub_f32_e32 v9, v89, v189
	v_sub_f32_e32 v10, v90, v189
	v_sub_f32_e32 v11, v91, v189
	v_sub_f32_e32 v12, v92, v189
	v_sub_f32_e32 v13, v93, v189
	v_sub_f32_e32 v14, v94, v189
	v_sub_f32_e32 v15, v95, v189
	v_sub_f32_e32 v16, v64, v189
	v_sub_f32_e32 v17, v65, v189
	v_sub_f32_e32 v18, v66, v189
	v_sub_f32_e32 v19, v67, v189
	v_sub_f32_e32 v20, v68, v189
	v_sub_f32_e32 v21, v69, v189
	v_sub_f32_e32 v22, v70, v189
	v_sub_f32_e32 v23, v71, v189
	v_sub_f32_e32 v24, v72, v189
	v_sub_f32_e32 v25, v73, v189
	v_sub_f32_e32 v26, v74, v189
	v_sub_f32_e32 v27, v75, v189
	v_sub_f32_e32 v28, v76, v189
	v_sub_f32_e32 v29, v77, v189
	v_sub_f32_e32 v30, v78, v189
	v_sub_f32_e32 v31, v79, v189
	v_exp_f32_e32 v112, v16
	v_exp_f32_e32 v113, v17
	v_exp_f32_e32 v114, v18
	v_exp_f32_e32 v115, v19
	v_exp_f32_e32 v116, v20
	v_exp_f32_e32 v117, v21
	v_exp_f32_e32 v118, v22
	v_exp_f32_e32 v119, v23
	v_exp_f32_e32 v120, v24
	v_exp_f32_e32 v121, v25
	v_exp_f32_e32 v122, v26
	v_exp_f32_e32 v123, v27
	v_exp_f32_e32 v124, v28
	v_exp_f32_e32 v125, v29
	v_exp_f32_e32 v126, v30
	v_exp_f32_e32 v127, v31
	v_exp_f32_e32 v96, v0
	v_exp_f32_e32 v97, v1
	v_exp_f32_e32 v98, v2
	v_exp_f32_e32 v99, v3
	v_exp_f32_e32 v100, v4
	v_exp_f32_e32 v101, v5
	v_exp_f32_e32 v102, v6
	v_exp_f32_e32 v103, v7
	v_exp_f32_e32 v104, v8
	v_exp_f32_e32 v105, v9
	v_exp_f32_e32 v106, v10
	v_exp_f32_e32 v107, v11
	v_exp_f32_e32 v108, v12
	v_exp_f32_e32 v109, v13
	v_exp_f32_e32 v110, v14
	v_exp_f32_e32 v111, v15
	s_waitcnt vmcnt(4)
	s_barrier
	v_cvt_pk_bf16_f32 v144, v112, v113
	v_cvt_pk_bf16_f32 v145, v114, v115
	v_cvt_pk_bf16_f32 v146, v116, v117
	v_cvt_pk_bf16_f32 v147, v118, v119
	v_cvt_pk_bf16_f32 v148, v120, v121
	v_cvt_pk_bf16_f32 v149, v122, v123
	v_cvt_pk_bf16_f32 v150, v124, v125
	v_cvt_pk_bf16_f32 v151, v126, v127
	v_cvt_pk_bf16_f32 v152, v96, v97
	v_cvt_pk_bf16_f32 v153, v98, v99
	v_cvt_pk_bf16_f32 v154, v100, v101
	v_cvt_pk_bf16_f32 v155, v102, v103
	v_cvt_pk_bf16_f32 v156, v104, v105
	v_cvt_pk_bf16_f32 v157, v106, v107
	v_cvt_pk_bf16_f32 v158, v108, v109
	v_cvt_pk_bf16_f32 v159, v110, v111
	s_setprio 2
	v_add_u32_e32 v188, v188, v184
	v_add_u32_e32 v12, 0, v188
	ds_read_b128 v[0:3], v12 offset:16384
	ds_read_b128 v[4:7], v12 offset:20480
	ds_read_b128 v[8:11], v12 offset:24576
	ds_read_b128 v[12:15], v12 offset:28672
	v_add_u32_e32 v187, v187, v184
	v_add_u32_e32 v16, 0, v187
	ds_read_b128 v[64:67], v16 offset:16384
	ds_read_b128 v[68:71], v16 offset:20480
	ds_read_b128 v[72:75], v16 offset:24576
	ds_read_b128 v[76:79], v16 offset:28672
	s_waitcnt lgkmcnt(0)
	v_mfma_f32_32x32x16_bf16 v[48:63], v[0:3], v[144:147], 0
	v_add_u32_e32 v186, v186, v184
	v_add_u32_e32 v92, 0, v186
	v_add_u32_e32 v184, v185, v184
	v_mfma_f32_32x32x16_bf16 v[32:47], v[4:7], v[144:147], 0
	v_mfma_f32_32x32x16_bf16 v[16:31], v[8:11], v[144:147], 0
	v_mfma_f32_32x32x16_bf16 v[0:15], v[12:15], v[144:147], 0
	ds_read_b128 v[80:83], v92 offset:16384
	ds_read_b128 v[84:87], v92 offset:20480
	ds_read_b128 v[88:91], v92 offset:24576
	ds_read_b128 v[92:95], v92 offset:28672
	v_mfma_f32_32x32x16_bf16 v[48:63], v[64:67], v[148:151], v[48:63]
	v_mfma_f32_32x32x16_bf16 v[32:47], v[68:71], v[148:151], v[32:47]
	v_mfma_f32_32x32x16_bf16 v[16:31], v[72:75], v[148:151], v[16:31]
	v_mfma_f32_32x32x16_bf16 v[0:15], v[76:79], v[148:151], v[0:15]
	v_add_u32_e32 v76, 0, v184
	ds_read_b128 v[64:67], v76 offset:16384
	ds_read_b128 v[68:71], v76 offset:20480
	ds_read_b128 v[72:75], v76 offset:24576
	ds_read_b128 v[76:79], v76 offset:28672
	s_waitcnt lgkmcnt(0)
	v_mfma_f32_32x32x16_bf16 v[48:63], v[80:83], v[152:155], v[48:63]
	v_mfma_f32_32x32x16_bf16 v[32:47], v[84:87], v[152:155], v[32:47]
	v_mfma_f32_32x32x16_bf16 v[16:31], v[88:91], v[152:155], v[16:31]
	v_mfma_f32_32x32x16_bf16 v[0:15], v[92:95], v[152:155], v[0:15]
	v_mfma_f32_32x32x16_bf16 v[48:63], v[64:67], v[156:159], v[48:63]
	v_mfma_f32_32x32x16_bf16 v[32:47], v[68:71], v[156:159], v[32:47]
	v_mfma_f32_32x32x16_bf16 v[16:31], v[72:75], v[156:159], v[16:31]
	v_mfma_f32_32x32x16_bf16 v[0:15], v[76:79], v[156:159], v[0:15]
	s_setprio 0
	s_cmp_gt_u32 s16, 1
	s_cbranch_scc0 .LBB0_375
	s_setprio 2
	v_add_u32_e32 v80, 0, v177
	ds_read_b128 v[196:199], v80 offset:32768
	ds_read_b128 v[200:203], v80 offset:40960
	v_add_u32_e32 v80, 0, v178
	ds_read_b128 v[204:207], v80 offset:32768
	ds_read_b128 v[208:211], v80 offset:40960
	v_add_u32_e32 v80, 0, v179
	ds_read_b128 v[212:215], v80 offset:32768
	ds_read_b128 v[216:219], v80 offset:40960
	v_add_u32_e32 v80, 0, v180
	ds_read_b128 v[220:223], v80 offset:32768
	ds_read_b128 v[224:227], v80 offset:40960
	s_waitcnt lgkmcnt(0)
	v_mfma_f32_32x32x16_bf16 v[80:95], v[196:199], v[128:131], v[232:247]
	v_mfma_f32_32x32x16_bf16 v[64:79], v[200:203], v[128:131], v[232:247]
	v_mfma_f32_32x32x16_bf16 v[80:95], v[204:207], v[132:135], v[80:95]
	v_mfma_f32_32x32x16_bf16 v[64:79], v[208:211], v[132:135], v[64:79]
	v_mfma_f32_32x32x16_bf16 v[80:95], v[212:215], v[136:139], v[80:95]
	v_mfma_f32_32x32x16_bf16 v[64:79], v[216:219], v[136:139], v[64:79]
	v_mfma_f32_32x32x16_bf16 v[80:95], v[220:223], v[140:143], v[80:95]
	v_mfma_f32_32x32x16_bf16 v[64:79], v[224:227], v[140:143], v[64:79]
	s_setprio 0
	s_branch .LBB0_376

; DI int crow(int i, int hh) { return (i & 3) + 8 * (i >> 2) + 4 * hh; }
; DI void diff_core(unsigned char* smem, const u16* qptr, const u16* kbase, const u16* vtbase, int vld,
;                   int ntb, int ntw, int nvalid, int ks0, const float* lut, int qpos, bool active, bool grpB,
;                   f32x16 (&O)[4], float& l_out) {
;     ...
;     if (lut != nullptr && t >= ntw - 3) {
;       const int base = t * 64 - qpos + 191;
; #pragma unroll
;       for (int kb = 0; kb < 2; ++kb)
; #pragma unroll
;         for (int i = 0; i < 16; ++i) S[kb][i] += lut[base + kb * 32 + crow(i, hh)];
;     }
;     ...
;       { const int tn = t + 2; dma(tn < tlast ? tn : tlast, tn & 3); }
;       if (act_t) softmax(t);
.LBB0_378:
	s_add_i32 s64, s62, 0x101
	s_add_i32 s101, s59, 0xffff8000
	s_and_b32 s101, s101, 0x18000
	s_cmp_lt_u32 s64, s16
	s_cselect_b64 s[0:1], -1, 0
	s_add_i32 s65, s62, 0x103
	s_min_i32 s65, s65, s58
	s_and_b32 s66, s59, 0x18000
	s_add_i32 s85, s6, s66
	s_lshl_b32 s66, s65, 6
	s_ashr_i32 s67, s66, 31
	s_lshl_b64 s[86:87], s[66:67], 11
	s_add_u32 s86, s14, s86
	s_addc_u32 s87, s15, s87
	s_lshl_b64 s[66:67], s[66:67], 1
	s_add_i32 s65, s85, 0x2000
	s_add_u32 s66, s20, s66
	s_mov_b32 m0, s85
	s_addc_u32 s67, s21, s67
	s_add_i32 s88, s85, 0x4000
	global_load_lds_dwordx4 v162, s[86:87]
	s_mov_b32 m0, s65
	s_add_i32 s89, s85, 0x6000
	global_load_lds_dwordx4 v170, s[86:87]
	s_mov_b32 m0, s88
	s_cmp_ge_u32 s64, s16
	global_load_lds_dwordx4 v166, s[66:67]
	s_mov_b32 m0, s89
	s_nop 0
	global_load_lds_dwordx4 v168, s[66:67]
	s_cbranch_scc1 .LBB0_384
	s_add_i32 s100, s59, 0xffff0000
	s_and_b32 s100, s100, 0x18000
	v_add_u32_e32 v248, s100, v188
	ds_read_b128 v[200:203], v248 offset:16384
	ds_read_b128 v[204:207], v248 offset:20480
	ds_read_b128 v[208:211], v248 offset:24576
	ds_read_b128 v[212:215], v248 offset:28672
	v_add_u32_e32 v249, s100, v187
	ds_read_b128 v[216:219], v249 offset:16384
	ds_read_b128 v[220:223], v249 offset:20480
	ds_read_b128 v[224:227], v249 offset:24576
	ds_read_b128 v[228:231], v249 offset:28672
	s_cmp_lt_i32 s64, s17
	s_cbranch_scc1 .LBB0_381
	ds_read2_b32 v[98:99], v96 offset1:1
	ds_read2_b32 v[100:101], v96 offset0:16 offset1:17
	ds_read2_b32 v[102:103], v96 offset0:18 offset1:19
	ds_read2_b32 v[104:105], v96 offset0:24 offset1:25
	ds_read2_b32 v[106:107], v96 offset0:26 offset1:27
	ds_read2_b32 v[108:109], v96 offset0:2 offset1:3
	ds_read2_b32 v[110:111], v96 offset0:8 offset1:9
	ds_read2_b32 v[112:113], v96 offset0:10 offset1:11
	s_waitcnt lgkmcnt(0)
	v_pk_add_f32 v[80:81], v[80:81], v[98:99]
	v_pk_add_f32 v[94:95], v[94:95], v[106:107]
	v_pk_add_f32 v[92:93], v[92:93], v[104:105]
	v_pk_add_f32 v[90:91], v[90:91], v[102:103]
	v_pk_add_f32 v[88:89], v[88:89], v[100:101]
	v_pk_add_f32 v[86:87], v[86:87], v[112:113]
	v_pk_add_f32 v[84:85], v[84:85], v[110:111]
	v_pk_add_f32 v[82:83], v[82:83], v[108:109]
	ds_read2_b32 v[98:99], v96 offset0:32 offset1:33
	ds_read2_b32 v[100:101], v96 offset0:48 offset1:49
	ds_read2_b32 v[102:103], v96 offset0:50 offset1:51
	ds_read2_b32 v[104:105], v96 offset0:56 offset1:57
	ds_read2_b32 v[106:107], v96 offset0:58 offset1:59
	ds_read2_b32 v[108:109], v96 offset0:34 offset1:35
	ds_read2_b32 v[110:111], v96 offset0:40 offset1:41
	ds_read2_b32 v[112:113], v96 offset0:42 offset1:43
	s_waitcnt lgkmcnt(0)
	v_pk_add_f32 v[64:65], v[64:65], v[98:99]
	v_pk_add_f32 v[78:79], v[78:79], v[106:107]
	v_pk_add_f32 v[76:77], v[76:77], v[104:105]
	v_pk_add_f32 v[74:75], v[74:75], v[102:103]
	v_pk_add_f32 v[72:73], v[72:73], v[100:101]
	v_pk_add_f32 v[70:71], v[70:71], v[112:113]
	v_pk_add_f32 v[68:69], v[68:69], v[110:111]
	v_pk_add_f32 v[66:67], v[66:67], v[108:109]
